# weight-conversion prologue: the 8 serialized gain loads (load, wait, multiply) of each tile group issued together with one wait
# speedup vs baseline: 1.0154x; 1.0043x over previous
.LBB0_1177:
	v_readlane_b32 s4, v252, 3
	v_readlane_b32 s5, v252, 4
	v_ashrrev_i32_e32 v17, 31, v16
	s_andn2_b64 vcc, exec, s[4:5]
	v_cndmask_b32_e64 v18, 0, 1, s[4:5]
	v_cmp_ne_u32_e64 s[6:7], 1, v18
	v_lshl_add_u64 v[16:17], v[16:17], 2, s[2:3]
	s_cbranch_vccnz .LBB0_1179
	global_load_dword v100, v[16:17], off
	global_load_dword v101, v[16:17], off offset:32
	global_load_dword v102, v[16:17], off offset:64
	global_load_dword v103, v[16:17], off offset:96
	global_load_dword v104, v[16:17], off offset:128
	global_load_dword v105, v[16:17], off offset:160
	global_load_dword v106, v[16:17], off offset:192
	global_load_dword v107, v[16:17], off offset:224
	s_waitcnt vmcnt(0)
	v_mul_f32_e32 v39, v39, v100
.LBB0_1179:
	s_movk_i32 s4, 0x104
	v_lshl_add_u32 v18, v36, 2, 0
	v_mul_lo_u32 v19, v2, s4
	v_add_u32_e32 v18, v18, v19
	s_and_b64 vcc, exec, s[6:7]
	s_waitcnt vmcnt(0)
	ds_write_b32 v18, v39
	s_cbranch_vccnz .LBB0_1181
	v_mul_f32_e32 v38, v38, v101
.LBB0_1181:
	s_and_b64 vcc, exec, s[6:7]
	ds_write_b32 v18, v38 offset:2080
	s_cbranch_vccnz .LBB0_1183
	v_mul_f32_e32 v37, v37, v102
.LBB0_1183:
	s_and_b64 vcc, exec, s[6:7]
	ds_write_b32 v18, v37 offset:4160
	s_cbranch_vccnz .LBB0_1185
	v_mul_f32_e32 v35, v35, v103
.LBB0_1185:
	s_and_b64 vcc, exec, s[6:7]
	ds_write_b32 v18, v35 offset:6240
	s_cbranch_vccnz .LBB0_1187
	v_mul_f32_e32 v34, v34, v104
.LBB0_1187:
	s_and_b64 vcc, exec, s[6:7]
	ds_write_b32 v18, v34 offset:8320
	s_cbranch_vccnz .LBB0_1189
	v_mul_f32_e32 v33, v33, v105
.LBB0_1189:
	s_and_b64 vcc, exec, s[6:7]
	ds_write_b32 v18, v33 offset:10400
	s_cbranch_vccnz .LBB0_1191
	v_mul_f32_e32 v32, v32, v106
.LBB0_1191:
	s_and_b64 vcc, exec, s[6:7]
	ds_write_b32 v18, v32 offset:12480
	s_cbranch_vccnz .LBB0_1193
	v_mul_f32_e32 v3, v3, v107

.LBB0_1275:
	v_readlane_b32 s4, v252, 9
	v_readlane_b32 s5, v252, 10
	v_ashrrev_i32_e32 v17, 31, v16
	s_andn2_b64 vcc, exec, s[4:5]
	v_cndmask_b32_e64 v18, 0, 1, s[4:5]
	v_cmp_ne_u32_e64 s[6:7], 1, v18
	v_lshl_add_u64 v[16:17], v[16:17], 2, s[2:3]
	s_cbranch_vccnz .LBB0_1277
	global_load_dword v100, v[16:17], off
	global_load_dword v101, v[16:17], off offset:32
	global_load_dword v102, v[16:17], off offset:64
	global_load_dword v103, v[16:17], off offset:96
	global_load_dword v104, v[16:17], off offset:128
	global_load_dword v105, v[16:17], off offset:160
	global_load_dword v106, v[16:17], off offset:192
	global_load_dword v107, v[16:17], off offset:224
	s_waitcnt vmcnt(0)
	v_mul_f32_e32 v39, v39, v100
